# phase 9 epilogue de-serialised: all 16 residual loads issued up front, per-group pack + line_pair + whole-line stores, batched partial-sum reduction
# speedup vs baseline: 1.0041x; 1.0041x over previous
.Lf9_next:
	s_and_b64 vcc, exec, s[6:7]
	s_mov_b32 s10, s38
	s_mov_b32 s8, s40
	s_mov_b64 s[50:51], s[46:47]
	s_mov_b64 s[48:49], s[44:45]
	s_cbranch_vccnz .LBB0_1030

.LBB0_997:
	ds_read_b128 v[128:131], v164
	ds_read_b128 v[132:135], v164 offset:1024
	ds_read_b128 v[152:155], v164 offset:2048
	ds_read_b128 v[156:159], v164 offset:3072
	s_add_u32 s28, s48, 0xfffe0080
	s_addc_u32 s29, s49, -1
	s_cmp_eq_u32 s79, 4
	s_cselect_b32 s53, s9, s29
	s_cselect_b32 s52, s41, s28
	s_cselect_b32 s51, s39, s78
	s_cselect_b32 s50, s76, s77
	v_lshl_add_u64 v[204:205], s[48:49], 0, v[144:145]
	s_add_i32 m0, s55, 0xc000
	ds_read_b128 v[168:171], v165
	ds_read_b128 v[172:175], v165 offset:1024
	ds_read_b128 v[176:179], v165 offset:2048
	ds_read_b128 v[180:183], v165 offset:3072
	ds_read_b128 v[184:187], v165 offset:4096
	ds_read_b128 v[188:191], v165 offset:5120
	ds_read_b128 v[196:199], v165 offset:6144
	ds_read_b128 v[200:203], v165 offset:7168
	global_load_lds_dwordx4 v[204:205], off
	v_lshl_add_u64 v[204:205], s[48:49], 0, v[146:147]
	s_add_i32 m0, s55, 0xe000
	s_nop 0
	global_load_lds_dwordx4 v[204:205], off
	s_waitcnt lgkmcnt(8)
	s_barrier
	s_waitcnt lgkmcnt(0)
	s_setprio 1
	s_waitcnt lgkmcnt(0)
	v_mfma_f32_16x16x32_bf16 v[124:127], v[128:131], v[168:171], v[124:127]
	v_mfma_f32_16x16x32_bf16 v[120:123], v[152:155], v[168:171], v[120:123]
	v_mfma_f32_16x16x32_bf16 v[108:111], v[128:131], v[176:179], v[108:111]
	v_mfma_f32_16x16x32_bf16 v[104:107], v[152:155], v[176:179], v[104:107]
	v_mfma_f32_16x16x32_bf16 v[92:95], v[128:131], v[184:187], v[92:95]
	v_mfma_f32_16x16x32_bf16 v[88:91], v[152:155], v[184:187], v[88:91]
	v_mfma_f32_16x16x32_bf16 v[76:79], v[128:131], v[196:199], v[76:79]
	v_mfma_f32_16x16x32_bf16 v[72:75], v[152:155], v[196:199], v[72:75]
	v_mfma_f32_16x16x32_bf16 v[124:127], v[132:135], v[172:175], v[124:127]
	v_mfma_f32_16x16x32_bf16 v[120:123], v[156:159], v[172:175], v[120:123]
	v_mfma_f32_16x16x32_bf16 v[108:111], v[132:135], v[180:183], v[108:111]
	v_mfma_f32_16x16x32_bf16 v[104:107], v[156:159], v[180:183], v[104:107]
	v_mfma_f32_16x16x32_bf16 v[92:95], v[132:135], v[188:191], v[92:95]
	v_mfma_f32_16x16x32_bf16 v[88:91], v[156:159], v[188:191], v[88:91]
	v_mfma_f32_16x16x32_bf16 v[76:79], v[132:135], v[200:203], v[76:79]
	v_mfma_f32_16x16x32_bf16 v[72:75], v[156:159], v[200:203], v[72:75]
	s_setprio 0
	s_barrier
	s_add_i32 s28, s65, s54
	v_lshl_add_u64 v[220:221], s[50:51], 0, v[138:139]
	s_mov_b32 m0, s28
	ds_read_b128 v[204:207], v166
	ds_read_b128 v[208:211], v166 offset:1024
	ds_read_b128 v[212:215], v166 offset:2048
	ds_read_b128 v[216:219], v166 offset:3072
	global_load_lds_dwordx4 v[220:221], off
	v_lshl_add_u64 v[222:223], s[50:51], 0, v[142:143]
	s_add_i32 m0, s28, 0x2000
	s_nop 0
	global_load_lds_dwordx4 v[222:223], off
	s_barrier
	s_waitcnt lgkmcnt(0)
	s_setprio 1
	s_waitcnt lgkmcnt(0)
	v_mfma_f32_16x16x32_bf16 v[116:119], v[204:207], v[168:171], v[116:119]
	v_mfma_f32_16x16x32_bf16 v[112:115], v[212:215], v[168:171], v[112:115]
	v_mfma_f32_16x16x32_bf16 v[100:103], v[204:207], v[176:179], v[100:103]
	v_mfma_f32_16x16x32_bf16 v[96:99], v[212:215], v[176:179], v[96:99]
	v_mfma_f32_16x16x32_bf16 v[84:87], v[204:207], v[184:187], v[84:87]
	v_mfma_f32_16x16x32_bf16 v[80:83], v[212:215], v[184:187], v[80:83]
	v_mfma_f32_16x16x32_bf16 v[68:71], v[204:207], v[196:199], v[68:71]
	v_mfma_f32_16x16x32_bf16 v[64:67], v[212:215], v[196:199], v[64:67]
	v_mfma_f32_16x16x32_bf16 v[116:119], v[208:211], v[172:175], v[116:119]
	v_mfma_f32_16x16x32_bf16 v[112:115], v[216:219], v[172:175], v[112:115]
	v_mfma_f32_16x16x32_bf16 v[100:103], v[208:211], v[180:183], v[100:103]
	v_mfma_f32_16x16x32_bf16 v[96:99], v[216:219], v[180:183], v[96:99]
	v_mfma_f32_16x16x32_bf16 v[84:87], v[208:211], v[188:191], v[84:87]
	v_mfma_f32_16x16x32_bf16 v[80:83], v[216:219], v[188:191], v[80:83]
	v_mfma_f32_16x16x32_bf16 v[68:71], v[208:211], v[200:203], v[68:71]
	v_mfma_f32_16x16x32_bf16 v[64:67], v[216:219], v[200:203], v[64:67]
	s_setprio 0
	s_mov_b32 m0, s55
	v_lshl_add_u64 v[224:225], s[52:53], 0, v[136:137]
	s_barrier
	ds_read_b128 v[168:171], v165 offset:16384
	ds_read_b128 v[172:175], v165 offset:17408
	ds_read_b128 v[176:179], v165 offset:18432
	ds_read_b128 v[180:183], v165 offset:19456
	ds_read_b128 v[184:187], v165 offset:20480
	ds_read_b128 v[188:191], v165 offset:21504
	ds_read_b128 v[196:199], v165 offset:22528
	ds_read_b128 v[200:203], v165 offset:23552
	global_load_lds_dwordx4 v[224:225], off
	v_lshl_add_u64 v[226:227], s[52:53], 0, v[140:141]
	s_mov_b32 m0, s56
	s_nop 0
	global_load_lds_dwordx4 v[226:227], off
	s_barrier
	s_waitcnt lgkmcnt(0)
	s_setprio 1
	s_waitcnt lgkmcnt(0)
	v_mfma_f32_16x16x32_bf16 v[60:63], v[128:131], v[168:171], v[60:63]
	v_mfma_f32_16x16x32_bf16 v[56:59], v[152:155], v[168:171], v[56:59]
	v_mfma_f32_16x16x32_bf16 v[44:47], v[128:131], v[176:179], v[44:47]
	v_mfma_f32_16x16x32_bf16 v[40:43], v[152:155], v[176:179], v[40:43]
	v_mfma_f32_16x16x32_bf16 v[28:31], v[128:131], v[184:187], v[28:31]
	v_mfma_f32_16x16x32_bf16 v[24:27], v[152:155], v[184:187], v[24:27]
	v_mfma_f32_16x16x32_bf16 v[12:15], v[128:131], v[196:199], v[12:15]
	v_mfma_f32_16x16x32_bf16 v[8:11], v[152:155], v[196:199], v[8:11]
	v_mfma_f32_16x16x32_bf16 v[60:63], v[132:135], v[172:175], v[60:63]
	v_mfma_f32_16x16x32_bf16 v[56:59], v[156:159], v[172:175], v[56:59]
	v_mfma_f32_16x16x32_bf16 v[44:47], v[132:135], v[180:183], v[44:47]
	v_mfma_f32_16x16x32_bf16 v[40:43], v[156:159], v[180:183], v[40:43]
	v_mfma_f32_16x16x32_bf16 v[28:31], v[132:135], v[188:191], v[28:31]
	v_mfma_f32_16x16x32_bf16 v[24:27], v[156:159], v[188:191], v[24:27]
	v_mfma_f32_16x16x32_bf16 v[12:15], v[132:135], v[200:203], v[12:15]
	v_mfma_f32_16x16x32_bf16 v[8:11], v[156:159], v[200:203], v[8:11]
	s_setprio 0
	s_barrier
	s_add_u32 s80, s50, 0x8000
	s_addc_u32 s81, s51, 0
	s_add_i32 s28, s66, s54
	v_lshl_add_u64 v[128:129], s[80:81], 0, v[138:139]
	s_mov_b32 m0, s28
	s_nop 0
	global_load_lds_dwordx4 v[128:129], off
	v_lshl_add_u64 v[128:129], s[80:81], 0, v[142:143]
	s_add_i32 m0, s28, 0x2000
	s_nop 0
	global_load_lds_dwordx4 v[128:129], off
	s_waitcnt vmcnt(6)
	s_barrier
	s_setprio 1
	v_mfma_f32_16x16x32_bf16 v[52:55], v[204:207], v[168:171], v[52:55]
	v_mfma_f32_16x16x32_bf16 v[48:51], v[212:215], v[168:171], v[48:51]
	v_mfma_f32_16x16x32_bf16 v[36:39], v[204:207], v[176:179], v[36:39]
	v_mfma_f32_16x16x32_bf16 v[32:35], v[212:215], v[176:179], v[32:35]
	v_mfma_f32_16x16x32_bf16 v[20:23], v[204:207], v[184:187], v[20:23]
	v_mfma_f32_16x16x32_bf16 v[16:19], v[212:215], v[184:187], v[16:19]
	v_mfma_f32_16x16x32_bf16 v[4:7], v[204:207], v[196:199], v[4:7]
	v_mfma_f32_16x16x32_bf16 v[0:3], v[212:215], v[196:199], v[0:3]
	v_mfma_f32_16x16x32_bf16 v[52:55], v[208:211], v[172:175], v[52:55]
	v_mfma_f32_16x16x32_bf16 v[48:51], v[216:219], v[172:175], v[48:51]
	v_mfma_f32_16x16x32_bf16 v[36:39], v[208:211], v[180:183], v[36:39]
	v_mfma_f32_16x16x32_bf16 v[32:35], v[216:219], v[180:183], v[32:35]
	v_mfma_f32_16x16x32_bf16 v[20:23], v[208:211], v[188:191], v[20:23]
	v_mfma_f32_16x16x32_bf16 v[16:19], v[216:219], v[188:191], v[16:19]
	v_mfma_f32_16x16x32_bf16 v[4:7], v[208:211], v[200:203], v[4:7]
	v_mfma_f32_16x16x32_bf16 v[0:3], v[216:219], v[200:203], v[0:3]
	s_setprio 0
	s_add_i32 s28, 0, 0x18000
	v_add_u32_e32 v156, s28, v161
	s_barrier
	ds_read_b128 v[128:131], v156
	ds_read_b128 v[132:135], v156 offset:1024
	ds_read_b128 v[152:155], v156 offset:2048
	ds_read_b128 v[156:159], v156 offset:3072
	s_add_u32 s52, s52, 0x20000
	s_addc_u32 s53, s53, 0
	s_mov_b32 m0, s57
	v_lshl_add_u64 v[204:205], s[52:53], 0, v[136:137]
	ds_read_b128 v[168:171], v165 offset:32768
	ds_read_b128 v[172:175], v165 offset:33792
	ds_read_b128 v[176:179], v165 offset:34816
	ds_read_b128 v[180:183], v165 offset:35840
	ds_read_b128 v[184:187], v165 offset:36864
	ds_read_b128 v[188:191], v165 offset:37888
	ds_read_b128 v[196:199], v165 offset:38912
	ds_read_b128 v[200:203], v165 offset:39936
	global_load_lds_dwordx4 v[204:205], off
	v_lshl_add_u64 v[204:205], s[52:53], 0, v[140:141]
	s_mov_b32 m0, s58
	s_nop 0
	global_load_lds_dwordx4 v[204:205], off
	s_waitcnt lgkmcnt(8)
	s_barrier
	s_waitcnt lgkmcnt(0)
	s_setprio 1
	s_waitcnt lgkmcnt(0)
	v_mfma_f32_16x16x32_bf16 v[124:127], v[128:131], v[168:171], v[124:127]
	v_mfma_f32_16x16x32_bf16 v[120:123], v[152:155], v[168:171], v[120:123]
	v_mfma_f32_16x16x32_bf16 v[108:111], v[128:131], v[176:179], v[108:111]
	v_mfma_f32_16x16x32_bf16 v[104:107], v[152:155], v[176:179], v[104:107]
	v_mfma_f32_16x16x32_bf16 v[92:95], v[128:131], v[184:187], v[92:95]
	v_mfma_f32_16x16x32_bf16 v[88:91], v[152:155], v[184:187], v[88:91]
	v_mfma_f32_16x16x32_bf16 v[76:79], v[128:131], v[196:199], v[76:79]
	v_mfma_f32_16x16x32_bf16 v[72:75], v[152:155], v[196:199], v[72:75]
	v_mfma_f32_16x16x32_bf16 v[124:127], v[132:135], v[172:175], v[124:127]
	v_mfma_f32_16x16x32_bf16 v[120:123], v[156:159], v[172:175], v[120:123]
	v_mfma_f32_16x16x32_bf16 v[108:111], v[132:135], v[180:183], v[108:111]
	v_mfma_f32_16x16x32_bf16 v[104:107], v[156:159], v[180:183], v[104:107]
	v_mfma_f32_16x16x32_bf16 v[92:95], v[132:135], v[188:191], v[92:95]
	v_mfma_f32_16x16x32_bf16 v[88:91], v[156:159], v[188:191], v[88:91]
	v_mfma_f32_16x16x32_bf16 v[76:79], v[132:135], v[200:203], v[76:79]
	v_mfma_f32_16x16x32_bf16 v[72:75], v[156:159], v[200:203], v[72:75]
	s_setprio 0
	s_barrier
	s_add_i32 s29, 0, 0x1c000
	s_add_i32 s28, s28, s54
	v_add_u32_e32 v195, s29, v161
	v_lshl_add_u64 v[220:221], v[220:221], 0, s[36:37]
	s_mov_b32 m0, s28
	ds_read_b128 v[204:207], v195
	ds_read_b128 v[208:211], v195 offset:1024
	ds_read_b128 v[212:215], v195 offset:2048
	ds_read_b128 v[216:219], v195 offset:3072
	global_load_lds_dwordx4 v[220:221], off
	v_lshl_add_u64 v[220:221], v[222:223], 0, s[36:37]
	s_add_i32 m0, s28, 0x2000
	s_nop 0
	global_load_lds_dwordx4 v[220:221], off
	s_barrier
	s_waitcnt lgkmcnt(0)
	s_setprio 1
	s_waitcnt lgkmcnt(0)
	v_mfma_f32_16x16x32_bf16 v[116:119], v[204:207], v[168:171], v[116:119]
	v_mfma_f32_16x16x32_bf16 v[112:115], v[212:215], v[168:171], v[112:115]
	v_mfma_f32_16x16x32_bf16 v[100:103], v[204:207], v[176:179], v[100:103]
	v_mfma_f32_16x16x32_bf16 v[96:99], v[212:215], v[176:179], v[96:99]
	v_mfma_f32_16x16x32_bf16 v[84:87], v[204:207], v[184:187], v[84:87]
	v_mfma_f32_16x16x32_bf16 v[80:83], v[212:215], v[184:187], v[80:83]
	v_mfma_f32_16x16x32_bf16 v[68:71], v[204:207], v[196:199], v[68:71]
	v_mfma_f32_16x16x32_bf16 v[64:67], v[212:215], v[196:199], v[64:67]
	v_mfma_f32_16x16x32_bf16 v[116:119], v[208:211], v[172:175], v[116:119]
	v_mfma_f32_16x16x32_bf16 v[112:115], v[216:219], v[172:175], v[112:115]
	v_mfma_f32_16x16x32_bf16 v[100:103], v[208:211], v[180:183], v[100:103]
	v_mfma_f32_16x16x32_bf16 v[96:99], v[216:219], v[180:183], v[96:99]
	v_mfma_f32_16x16x32_bf16 v[84:87], v[208:211], v[188:191], v[84:87]
	v_mfma_f32_16x16x32_bf16 v[80:83], v[216:219], v[188:191], v[80:83]
	v_mfma_f32_16x16x32_bf16 v[68:71], v[208:211], v[200:203], v[68:71]
	v_mfma_f32_16x16x32_bf16 v[64:67], v[216:219], v[200:203], v[64:67]
	s_setprio 0
	s_mov_b32 m0, s62
	v_lshl_add_u64 v[220:221], v[224:225], 0, s[36:37]
	s_barrier
	ds_read_b128 v[168:171], v165 offset:49152
	ds_read_b128 v[172:175], v165 offset:50176
	ds_read_b128 v[176:179], v165 offset:51200
	ds_read_b128 v[180:183], v165 offset:52224
	ds_read_b128 v[184:187], v165 offset:53248
	ds_read_b128 v[188:191], v165 offset:54272
	ds_read_b128 v[196:199], v165 offset:55296
	ds_read_b128 v[200:203], v165 offset:56320
	global_load_lds_dwordx4 v[220:221], off
	v_lshl_add_u64 v[220:221], v[226:227], 0, s[36:37]
	s_mov_b32 m0, s63
	s_nop 0
	global_load_lds_dwordx4 v[220:221], off
	s_barrier
	s_waitcnt lgkmcnt(0)
	s_setprio 1
	s_waitcnt lgkmcnt(0)
	v_mfma_f32_16x16x32_bf16 v[60:63], v[128:131], v[168:171], v[60:63]
	v_mfma_f32_16x16x32_bf16 v[56:59], v[152:155], v[168:171], v[56:59]
	v_mfma_f32_16x16x32_bf16 v[44:47], v[128:131], v[176:179], v[44:47]
	v_mfma_f32_16x16x32_bf16 v[40:43], v[152:155], v[176:179], v[40:43]
	v_mfma_f32_16x16x32_bf16 v[28:31], v[128:131], v[184:187], v[28:31]
	v_mfma_f32_16x16x32_bf16 v[24:27], v[152:155], v[184:187], v[24:27]
	v_mfma_f32_16x16x32_bf16 v[12:15], v[128:131], v[196:199], v[12:15]
	v_mfma_f32_16x16x32_bf16 v[8:11], v[152:155], v[196:199], v[8:11]
	v_mfma_f32_16x16x32_bf16 v[60:63], v[132:135], v[172:175], v[60:63]
	v_mfma_f32_16x16x32_bf16 v[56:59], v[156:159], v[172:175], v[56:59]
	v_mfma_f32_16x16x32_bf16 v[44:47], v[132:135], v[180:183], v[44:47]
	v_mfma_f32_16x16x32_bf16 v[40:43], v[156:159], v[180:183], v[40:43]
	v_mfma_f32_16x16x32_bf16 v[28:31], v[132:135], v[188:191], v[28:31]
	v_mfma_f32_16x16x32_bf16 v[24:27], v[156:159], v[188:191], v[24:27]
	v_mfma_f32_16x16x32_bf16 v[12:15], v[132:135], v[200:203], v[12:15]
	v_mfma_f32_16x16x32_bf16 v[8:11], v[156:159], v[200:203], v[8:11]
	s_setprio 0
	s_barrier
	s_add_u32 s50, s50, 0x8080
	s_addc_u32 s51, s51, 0
	s_add_i32 s28, s29, s54
	v_lshl_add_u64 v[128:129], s[50:51], 0, v[138:139]
	s_mov_b32 m0, s28
	s_nop 0
	global_load_lds_dwordx4 v[128:129], off
	v_lshl_add_u64 v[128:129], s[50:51], 0, v[142:143]
	s_add_i32 m0, s28, 0x2000
	s_nop 0
	global_load_lds_dwordx4 v[128:129], off
	s_waitcnt vmcnt(6)
	s_barrier
	s_setprio 1
	v_mfma_f32_16x16x32_bf16 v[52:55], v[204:207], v[168:171], v[52:55]
	v_mfma_f32_16x16x32_bf16 v[48:51], v[212:215], v[168:171], v[48:51]
	v_mfma_f32_16x16x32_bf16 v[36:39], v[204:207], v[176:179], v[36:39]
	v_mfma_f32_16x16x32_bf16 v[32:35], v[212:215], v[176:179], v[32:35]
	v_mfma_f32_16x16x32_bf16 v[20:23], v[204:207], v[184:187], v[20:23]
	v_mfma_f32_16x16x32_bf16 v[16:19], v[212:215], v[184:187], v[16:19]
	v_mfma_f32_16x16x32_bf16 v[4:7], v[204:207], v[196:199], v[4:7]
	v_mfma_f32_16x16x32_bf16 v[0:3], v[212:215], v[196:199], v[0:3]
	v_mfma_f32_16x16x32_bf16 v[52:55], v[208:211], v[172:175], v[52:55]
	v_mfma_f32_16x16x32_bf16 v[48:51], v[216:219], v[172:175], v[48:51]
	v_mfma_f32_16x16x32_bf16 v[36:39], v[208:211], v[180:183], v[36:39]
	v_mfma_f32_16x16x32_bf16 v[32:35], v[216:219], v[180:183], v[32:35]
	v_mfma_f32_16x16x32_bf16 v[20:23], v[208:211], v[188:191], v[20:23]
	v_mfma_f32_16x16x32_bf16 v[16:19], v[216:219], v[188:191], v[16:19]
	v_mfma_f32_16x16x32_bf16 v[4:7], v[208:211], v[200:203], v[4:7]
	v_mfma_f32_16x16x32_bf16 v[0:3], v[216:219], v[200:203], v[0:3]
	s_setprio 0
	s_add_i32 s79, s79, 2
	s_add_u32 s48, s48, 0x100
	s_addc_u32 s49, s49, 0
	s_add_u32 s77, s77, 0x100
	s_addc_u32 s78, s78, 0
	s_cmp_gt_u32 s79, 5
	s_barrier
	s_cbranch_scc0 .LBB0_997
	v_lshl_add_u32 v189, s8, 8, v160
	v_lshl_or_b32 v188, s10, 8, v162
	s_mov_b32 s87, 0xffff0000
	v_lshlrev_b32_e32 v128, 11, v189
	v_lshl_add_u32 v128, v188, 1, v128
	s_mov_b64 s[76:77], s[42:43]
	global_load_dwordx4 v[196:199], v128, s[76:77]
	global_load_dwordx4 v[200:203], v128, s[76:77] offset:64
	s_add_u32 s76, s76, 0x8000
	s_addc_u32 s77, s77, 0
	global_load_dwordx4 v[204:207], v128, s[76:77]
	global_load_dwordx4 v[208:211], v128, s[76:77] offset:64
	s_add_u32 s76, s76, 0x8000
	s_addc_u32 s77, s77, 0
	global_load_dwordx4 v[212:215], v128, s[76:77]
	global_load_dwordx4 v[216:219], v128, s[76:77] offset:64
	s_add_u32 s76, s76, 0x8000
	s_addc_u32 s77, s77, 0
	global_load_dwordx4 v[220:223], v128, s[76:77]
	global_load_dwordx4 v[224:227], v128, s[76:77] offset:64
	s_add_u32 s76, s76, 0x28000
	s_addc_u32 s77, s77, 0
	global_load_dwordx4 v[228:231], v128, s[76:77]
	global_load_dwordx4 v[232:235], v128, s[76:77] offset:64
	s_add_u32 s76, s76, 0x8000
	s_addc_u32 s77, s77, 0
	global_load_dwordx4 v[236:239], v128, s[76:77]
	global_load_dwordx4 v[168:171], v128, s[76:77] offset:64
	s_add_u32 s76, s76, 0x8000
	s_addc_u32 s77, s77, 0
	global_load_dwordx4 v[172:175], v128, s[76:77]
	global_load_dwordx4 v[176:179], v128, s[76:77] offset:64
	s_add_u32 s76, s76, 0x8000
	s_addc_u32 s77, s77, 0
	global_load_dwordx4 v[180:183], v128, s[76:77]
	global_load_dwordx4 v[184:187], v128, s[76:77] offset:64
	s_lshl_b32 s28, s10, 4
	s_lshl_b32 s29, s61, 2
	s_add_i32 s28, s28, s29
	v_lshl_add_u32 v130, v189, 6, s28
	v_xor_b32_e32 v134, 16, v167
	v_xor_b32_e32 v135, 32, v167
	v_lshlrev_b32_e32 v134, 2, v134
	v_lshlrev_b32_e32 v135, 2, v135
	s_add_u32 s80, s0, 0x2000
	s_addc_u32 s81, s1, 0
	s_mov_b64 s[78:79], s[68:69]
	v_add_u32_e32 v131, 0xffffc040, v128
	v_add_u32_e32 v132, 0x4000, v128
	v_add_u32_e32 v133, 64, v128
	v_cndmask_b32_e64 v129, v131, v128, s[4:5]
	v_cndmask_b32_e64 v131, v133, v132, s[4:5]
	s_waitcnt vmcnt(14)
	v_lshlrev_b32_e32 v190, 16, v196
	v_and_b32_e32 v191, s87, v196
	v_pk_add_f32 v[124:125], v[124:125], v[190:191]
	v_lshlrev_b32_e32 v192, 16, v197
	v_and_b32_e32 v193, s87, v197
	v_pk_add_f32 v[126:127], v[126:127], v[192:193]
	v_lshlrev_b32_e32 v190, 16, v198
	v_and_b32_e32 v191, s87, v198
	v_pk_add_f32 v[120:121], v[120:121], v[190:191]
	v_lshlrev_b32_e32 v192, 16, v199
	v_and_b32_e32 v193, s87, v199
	v_pk_add_f32 v[122:123], v[122:123], v[192:193]
	v_lshlrev_b32_e32 v190, 16, v200
	v_and_b32_e32 v191, s87, v200
	v_pk_add_f32 v[116:117], v[116:117], v[190:191]
	v_lshlrev_b32_e32 v192, 16, v201
	v_and_b32_e32 v193, s87, v201
	v_pk_add_f32 v[118:119], v[118:119], v[192:193]
	v_lshlrev_b32_e32 v190, 16, v202
	v_and_b32_e32 v191, s87, v202
	v_pk_add_f32 v[112:113], v[112:113], v[190:191]
	v_lshlrev_b32_e32 v192, 16, v203
	v_and_b32_e32 v193, s87, v203
	v_pk_add_f32 v[114:115], v[114:115], v[192:193]
	v_cvt_pk_bf16_f32 v196, v124, v125
	v_cvt_pk_bf16_f32 v197, v126, v127
	v_cvt_pk_bf16_f32 v198, v120, v121
	v_cvt_pk_bf16_f32 v199, v122, v123
	v_cvt_pk_bf16_f32 v200, v116, v117
	v_cvt_pk_bf16_f32 v201, v118, v119
	v_cvt_pk_bf16_f32 v202, v112, v113
	v_cvt_pk_bf16_f32 v203, v114, v115
	v_mul_f32_e32 v152, v120, v120
	v_mul_f32_e32 v188, v112, v112
	v_fmac_f32_e32 v152, v121, v121
	v_fmac_f32_e32 v188, v113, v113
	v_fmac_f32_e32 v152, v122, v122
	v_fmac_f32_e32 v188, v114, v114
	v_fmac_f32_e32 v152, v123, v123
	v_fmac_f32_e32 v188, v115, v115
	v_fmac_f32_e32 v152, v124, v124
	v_fmac_f32_e32 v188, v116, v116
	v_fmac_f32_e32 v152, v125, v125
	v_fmac_f32_e32 v188, v117, v117
	v_fmac_f32_e32 v152, v126, v126
	v_fmac_f32_e32 v188, v118, v118
	v_fmac_f32_e32 v152, v127, v127
	v_fmac_f32_e32 v188, v119, v119
	v_add_f32_e32 v152, v152, v188
	v_cndmask_b32_e64 v112, v196, v200, s[4:5]
	v_cndmask_b32_e64 v113, v197, v201, s[4:5]
	v_cndmask_b32_e64 v114, v198, v202, s[4:5]
	v_cndmask_b32_e64 v115, v199, v203, s[4:5]
	v_mov_b32_dpp v116, v112 row_ror:8 row_mask:0xf bank_mask:0xf
	v_mov_b32_dpp v117, v113 row_ror:8 row_mask:0xf bank_mask:0xf
	v_mov_b32_dpp v118, v114 row_ror:8 row_mask:0xf bank_mask:0xf
	v_mov_b32_dpp v119, v115 row_ror:8 row_mask:0xf bank_mask:0xf
	v_cndmask_b32_e64 v200, v200, v116, s[4:5]
	v_cndmask_b32_e64 v196, v116, v196, s[4:5]
	v_cndmask_b32_e64 v201, v201, v117, s[4:5]
	v_cndmask_b32_e64 v197, v117, v197, s[4:5]
	v_cndmask_b32_e64 v202, v202, v118, s[4:5]
	v_cndmask_b32_e64 v198, v118, v198, s[4:5]
	v_cndmask_b32_e64 v203, v203, v119, s[4:5]
	v_cndmask_b32_e64 v199, v119, v199, s[4:5]
	global_store_dwordx4 v129, v[196:199], s[78:79]
	global_store_dwordx4 v131, v[200:203], s[78:79]
	s_add_u32 s78, s78, 0x8000
	s_addc_u32 s79, s79, 0
	s_waitcnt vmcnt(14)
	v_lshlrev_b32_e32 v190, 16, v204
	v_and_b32_e32 v191, s87, v204
	v_pk_add_f32 v[108:109], v[108:109], v[190:191]
	v_lshlrev_b32_e32 v192, 16, v205
	v_and_b32_e32 v193, s87, v205
	v_pk_add_f32 v[110:111], v[110:111], v[192:193]
	v_lshlrev_b32_e32 v190, 16, v206
	v_and_b32_e32 v191, s87, v206
	v_pk_add_f32 v[104:105], v[104:105], v[190:191]
	v_lshlrev_b32_e32 v192, 16, v207
	v_and_b32_e32 v193, s87, v207
	v_pk_add_f32 v[106:107], v[106:107], v[192:193]
	v_lshlrev_b32_e32 v190, 16, v208
	v_and_b32_e32 v191, s87, v208
	v_pk_add_f32 v[100:101], v[100:101], v[190:191]
	v_lshlrev_b32_e32 v192, 16, v209
	v_and_b32_e32 v193, s87, v209
	v_pk_add_f32 v[102:103], v[102:103], v[192:193]
	v_lshlrev_b32_e32 v190, 16, v210
	v_and_b32_e32 v191, s87, v210
	v_pk_add_f32 v[96:97], v[96:97], v[190:191]
	v_lshlrev_b32_e32 v192, 16, v211
	v_and_b32_e32 v193, s87, v211
	v_pk_add_f32 v[98:99], v[98:99], v[192:193]
	v_cvt_pk_bf16_f32 v204, v108, v109
	v_cvt_pk_bf16_f32 v205, v110, v111
	v_cvt_pk_bf16_f32 v206, v104, v105
	v_cvt_pk_bf16_f32 v207, v106, v107
	v_cvt_pk_bf16_f32 v208, v100, v101
	v_cvt_pk_bf16_f32 v209, v102, v103
	v_cvt_pk_bf16_f32 v210, v96, v97
	v_cvt_pk_bf16_f32 v211, v98, v99
	v_mul_f32_e32 v153, v104, v104
	v_mul_f32_e32 v188, v96, v96
	v_fmac_f32_e32 v153, v105, v105
	v_fmac_f32_e32 v188, v97, v97
	v_fmac_f32_e32 v153, v106, v106
	v_fmac_f32_e32 v188, v98, v98
	v_fmac_f32_e32 v153, v107, v107
	v_fmac_f32_e32 v188, v99, v99
	v_fmac_f32_e32 v153, v108, v108
	v_fmac_f32_e32 v188, v100, v100
	v_fmac_f32_e32 v153, v109, v109
	v_fmac_f32_e32 v188, v101, v101
	v_fmac_f32_e32 v153, v110, v110
	v_fmac_f32_e32 v188, v102, v102
	v_fmac_f32_e32 v153, v111, v111
	v_fmac_f32_e32 v188, v103, v103
	v_add_f32_e32 v153, v153, v188
	v_cndmask_b32_e64 v96, v204, v208, s[4:5]
	v_cndmask_b32_e64 v97, v205, v209, s[4:5]
	v_cndmask_b32_e64 v98, v206, v210, s[4:5]
	v_cndmask_b32_e64 v99, v207, v211, s[4:5]
	v_mov_b32_dpp v100, v96 row_ror:8 row_mask:0xf bank_mask:0xf
	v_mov_b32_dpp v101, v97 row_ror:8 row_mask:0xf bank_mask:0xf
	v_mov_b32_dpp v102, v98 row_ror:8 row_mask:0xf bank_mask:0xf
	v_mov_b32_dpp v103, v99 row_ror:8 row_mask:0xf bank_mask:0xf
	v_cndmask_b32_e64 v208, v208, v100, s[4:5]
	v_cndmask_b32_e64 v204, v100, v204, s[4:5]
	v_cndmask_b32_e64 v209, v209, v101, s[4:5]
	v_cndmask_b32_e64 v205, v101, v205, s[4:5]
	v_cndmask_b32_e64 v210, v210, v102, s[4:5]
	v_cndmask_b32_e64 v206, v102, v206, s[4:5]
	v_cndmask_b32_e64 v211, v211, v103, s[4:5]
	v_cndmask_b32_e64 v207, v103, v207, s[4:5]
	global_store_dwordx4 v129, v[204:207], s[78:79]
	global_store_dwordx4 v131, v[208:211], s[78:79]
	s_add_u32 s78, s78, 0x8000
	s_addc_u32 s79, s79, 0
	s_waitcnt vmcnt(14)
	v_lshlrev_b32_e32 v190, 16, v212
	v_and_b32_e32 v191, s87, v212
	v_pk_add_f32 v[92:93], v[92:93], v[190:191]
	v_lshlrev_b32_e32 v192, 16, v213
	v_and_b32_e32 v193, s87, v213
	v_pk_add_f32 v[94:95], v[94:95], v[192:193]
	v_lshlrev_b32_e32 v190, 16, v214
	v_and_b32_e32 v191, s87, v214
	v_pk_add_f32 v[88:89], v[88:89], v[190:191]
	v_lshlrev_b32_e32 v192, 16, v215
	v_and_b32_e32 v193, s87, v215
	v_pk_add_f32 v[90:91], v[90:91], v[192:193]
	v_lshlrev_b32_e32 v190, 16, v216
	v_and_b32_e32 v191, s87, v216
	v_pk_add_f32 v[84:85], v[84:85], v[190:191]
	v_lshlrev_b32_e32 v192, 16, v217
	v_and_b32_e32 v193, s87, v217
	v_pk_add_f32 v[86:87], v[86:87], v[192:193]
	v_lshlrev_b32_e32 v190, 16, v218
	v_and_b32_e32 v191, s87, v218
	v_pk_add_f32 v[80:81], v[80:81], v[190:191]
	v_lshlrev_b32_e32 v192, 16, v219
	v_and_b32_e32 v193, s87, v219
	v_pk_add_f32 v[82:83], v[82:83], v[192:193]
	v_cvt_pk_bf16_f32 v212, v92, v93
	v_cvt_pk_bf16_f32 v213, v94, v95
	v_cvt_pk_bf16_f32 v214, v88, v89
	v_cvt_pk_bf16_f32 v215, v90, v91
	v_cvt_pk_bf16_f32 v216, v84, v85
	v_cvt_pk_bf16_f32 v217, v86, v87
	v_cvt_pk_bf16_f32 v218, v80, v81
	v_cvt_pk_bf16_f32 v219, v82, v83
	v_mul_f32_e32 v154, v88, v88
	v_mul_f32_e32 v188, v80, v80
	v_fmac_f32_e32 v154, v89, v89
	v_fmac_f32_e32 v188, v81, v81
	v_fmac_f32_e32 v154, v90, v90
	v_fmac_f32_e32 v188, v82, v82
	v_fmac_f32_e32 v154, v91, v91
	v_fmac_f32_e32 v188, v83, v83
	v_fmac_f32_e32 v154, v92, v92
	v_fmac_f32_e32 v188, v84, v84
	v_fmac_f32_e32 v154, v93, v93
	v_fmac_f32_e32 v188, v85, v85
	v_fmac_f32_e32 v154, v94, v94
	v_fmac_f32_e32 v188, v86, v86
	v_fmac_f32_e32 v154, v95, v95
	v_fmac_f32_e32 v188, v87, v87
	v_add_f32_e32 v154, v154, v188
	v_cndmask_b32_e64 v80, v212, v216, s[4:5]
	v_cndmask_b32_e64 v81, v213, v217, s[4:5]
	v_cndmask_b32_e64 v82, v214, v218, s[4:5]
	v_cndmask_b32_e64 v83, v215, v219, s[4:5]
	v_mov_b32_dpp v84, v80 row_ror:8 row_mask:0xf bank_mask:0xf
	v_mov_b32_dpp v85, v81 row_ror:8 row_mask:0xf bank_mask:0xf
	v_mov_b32_dpp v86, v82 row_ror:8 row_mask:0xf bank_mask:0xf
	v_mov_b32_dpp v87, v83 row_ror:8 row_mask:0xf bank_mask:0xf
	v_cndmask_b32_e64 v216, v216, v84, s[4:5]
	v_cndmask_b32_e64 v212, v84, v212, s[4:5]
	v_cndmask_b32_e64 v217, v217, v85, s[4:5]
	v_cndmask_b32_e64 v213, v85, v213, s[4:5]
	v_cndmask_b32_e64 v218, v218, v86, s[4:5]
	v_cndmask_b32_e64 v214, v86, v214, s[4:5]
	v_cndmask_b32_e64 v219, v219, v87, s[4:5]
	v_cndmask_b32_e64 v215, v87, v215, s[4:5]
	global_store_dwordx4 v129, v[212:215], s[78:79]
	global_store_dwordx4 v131, v[216:219], s[78:79]
	s_add_u32 s78, s78, 0x8000
	s_addc_u32 s79, s79, 0
	s_waitcnt vmcnt(14)
	v_lshlrev_b32_e32 v190, 16, v220
	v_and_b32_e32 v191, s87, v220
	v_pk_add_f32 v[76:77], v[76:77], v[190:191]
	v_lshlrev_b32_e32 v192, 16, v221
	v_and_b32_e32 v193, s87, v221
	v_pk_add_f32 v[78:79], v[78:79], v[192:193]
	v_lshlrev_b32_e32 v190, 16, v222
	v_and_b32_e32 v191, s87, v222
	v_pk_add_f32 v[72:73], v[72:73], v[190:191]
	v_lshlrev_b32_e32 v192, 16, v223
	v_and_b32_e32 v193, s87, v223
	v_pk_add_f32 v[74:75], v[74:75], v[192:193]
	v_lshlrev_b32_e32 v190, 16, v224
	v_and_b32_e32 v191, s87, v224
	v_pk_add_f32 v[68:69], v[68:69], v[190:191]
	v_lshlrev_b32_e32 v192, 16, v225
	v_and_b32_e32 v193, s87, v225
	v_pk_add_f32 v[70:71], v[70:71], v[192:193]
	v_lshlrev_b32_e32 v190, 16, v226
	v_and_b32_e32 v191, s87, v226
	v_pk_add_f32 v[64:65], v[64:65], v[190:191]
	v_lshlrev_b32_e32 v192, 16, v227
	v_and_b32_e32 v193, s87, v227
	v_pk_add_f32 v[66:67], v[66:67], v[192:193]
	v_cvt_pk_bf16_f32 v220, v76, v77
	v_cvt_pk_bf16_f32 v221, v78, v79
	v_cvt_pk_bf16_f32 v222, v72, v73
	v_cvt_pk_bf16_f32 v223, v74, v75
	v_cvt_pk_bf16_f32 v224, v68, v69
	v_cvt_pk_bf16_f32 v225, v70, v71
	v_cvt_pk_bf16_f32 v226, v64, v65
	v_cvt_pk_bf16_f32 v227, v66, v67
	v_mul_f32_e32 v155, v72, v72
	v_mul_f32_e32 v188, v64, v64
	v_fmac_f32_e32 v155, v73, v73
	v_fmac_f32_e32 v188, v65, v65
	v_fmac_f32_e32 v155, v74, v74
	v_fmac_f32_e32 v188, v66, v66
	v_fmac_f32_e32 v155, v75, v75
	v_fmac_f32_e32 v188, v67, v67
	v_fmac_f32_e32 v155, v76, v76
	v_fmac_f32_e32 v188, v68, v68
	v_fmac_f32_e32 v155, v77, v77
	v_fmac_f32_e32 v188, v69, v69
	v_fmac_f32_e32 v155, v78, v78
	v_fmac_f32_e32 v188, v70, v70
	v_fmac_f32_e32 v155, v79, v79
	v_fmac_f32_e32 v188, v71, v71
	v_add_f32_e32 v155, v155, v188
	v_cndmask_b32_e64 v64, v220, v224, s[4:5]
	v_cndmask_b32_e64 v65, v221, v225, s[4:5]
	v_cndmask_b32_e64 v66, v222, v226, s[4:5]
	v_cndmask_b32_e64 v67, v223, v227, s[4:5]
	v_mov_b32_dpp v68, v64 row_ror:8 row_mask:0xf bank_mask:0xf
	v_mov_b32_dpp v69, v65 row_ror:8 row_mask:0xf bank_mask:0xf
	v_mov_b32_dpp v70, v66 row_ror:8 row_mask:0xf bank_mask:0xf
	v_mov_b32_dpp v71, v67 row_ror:8 row_mask:0xf bank_mask:0xf
	v_cndmask_b32_e64 v224, v224, v68, s[4:5]
	v_cndmask_b32_e64 v220, v68, v220, s[4:5]
	v_cndmask_b32_e64 v225, v225, v69, s[4:5]
	v_cndmask_b32_e64 v221, v69, v221, s[4:5]
	v_cndmask_b32_e64 v226, v226, v70, s[4:5]
	v_cndmask_b32_e64 v222, v70, v222, s[4:5]
	v_cndmask_b32_e64 v227, v227, v71, s[4:5]
	v_cndmask_b32_e64 v223, v71, v223, s[4:5]
	global_store_dwordx4 v129, v[220:223], s[78:79]
	global_store_dwordx4 v131, v[224:227], s[78:79]
	s_add_u32 s78, s78, 0x28000
	s_addc_u32 s79, s79, 0
	s_waitcnt vmcnt(14)
	v_lshlrev_b32_e32 v190, 16, v228
	v_and_b32_e32 v191, s87, v228
	v_pk_add_f32 v[60:61], v[60:61], v[190:191]
	v_lshlrev_b32_e32 v192, 16, v229
	v_and_b32_e32 v193, s87, v229
	v_pk_add_f32 v[62:63], v[62:63], v[192:193]
	v_lshlrev_b32_e32 v190, 16, v230
	v_and_b32_e32 v191, s87, v230
	v_pk_add_f32 v[56:57], v[56:57], v[190:191]
	v_lshlrev_b32_e32 v192, 16, v231
	v_and_b32_e32 v193, s87, v231
	v_pk_add_f32 v[58:59], v[58:59], v[192:193]
	v_lshlrev_b32_e32 v190, 16, v232
	v_and_b32_e32 v191, s87, v232
	v_pk_add_f32 v[52:53], v[52:53], v[190:191]
	v_lshlrev_b32_e32 v192, 16, v233
	v_and_b32_e32 v193, s87, v233
	v_pk_add_f32 v[54:55], v[54:55], v[192:193]
	v_lshlrev_b32_e32 v190, 16, v234
	v_and_b32_e32 v191, s87, v234
	v_pk_add_f32 v[48:49], v[48:49], v[190:191]
	v_lshlrev_b32_e32 v192, 16, v235
	v_and_b32_e32 v193, s87, v235
	v_pk_add_f32 v[50:51], v[50:51], v[192:193]
	v_cvt_pk_bf16_f32 v228, v60, v61
	v_cvt_pk_bf16_f32 v229, v62, v63
	v_cvt_pk_bf16_f32 v230, v56, v57
	v_cvt_pk_bf16_f32 v231, v58, v59
	v_cvt_pk_bf16_f32 v232, v52, v53
	v_cvt_pk_bf16_f32 v233, v54, v55
	v_cvt_pk_bf16_f32 v234, v48, v49
	v_cvt_pk_bf16_f32 v235, v50, v51
	v_mul_f32_e32 v156, v56, v56
	v_mul_f32_e32 v188, v48, v48
	v_fmac_f32_e32 v156, v57, v57
	v_fmac_f32_e32 v188, v49, v49
	v_fmac_f32_e32 v156, v58, v58
	v_fmac_f32_e32 v188, v50, v50
	v_fmac_f32_e32 v156, v59, v59
	v_fmac_f32_e32 v188, v51, v51
	v_fmac_f32_e32 v156, v60, v60
	v_fmac_f32_e32 v188, v52, v52
	v_fmac_f32_e32 v156, v61, v61
	v_fmac_f32_e32 v188, v53, v53
	v_fmac_f32_e32 v156, v62, v62
	v_fmac_f32_e32 v188, v54, v54
	v_fmac_f32_e32 v156, v63, v63
	v_fmac_f32_e32 v188, v55, v55
	v_add_f32_e32 v156, v156, v188
	v_cndmask_b32_e64 v48, v228, v232, s[4:5]
	v_cndmask_b32_e64 v49, v229, v233, s[4:5]
	v_cndmask_b32_e64 v50, v230, v234, s[4:5]
	v_cndmask_b32_e64 v51, v231, v235, s[4:5]
	v_mov_b32_dpp v52, v48 row_ror:8 row_mask:0xf bank_mask:0xf
	v_mov_b32_dpp v53, v49 row_ror:8 row_mask:0xf bank_mask:0xf
	v_mov_b32_dpp v54, v50 row_ror:8 row_mask:0xf bank_mask:0xf
	v_mov_b32_dpp v55, v51 row_ror:8 row_mask:0xf bank_mask:0xf
	v_cndmask_b32_e64 v232, v232, v52, s[4:5]
	v_cndmask_b32_e64 v228, v52, v228, s[4:5]
	v_cndmask_b32_e64 v233, v233, v53, s[4:5]
	v_cndmask_b32_e64 v229, v53, v229, s[4:5]
	v_cndmask_b32_e64 v234, v234, v54, s[4:5]
	v_cndmask_b32_e64 v230, v54, v230, s[4:5]
	v_cndmask_b32_e64 v235, v235, v55, s[4:5]
	v_cndmask_b32_e64 v231, v55, v231, s[4:5]
	global_store_dwordx4 v129, v[228:231], s[78:79]
	global_store_dwordx4 v131, v[232:235], s[78:79]
	s_add_u32 s78, s78, 0x8000
	s_addc_u32 s79, s79, 0
	s_waitcnt vmcnt(14)
	v_lshlrev_b32_e32 v190, 16, v236
	v_and_b32_e32 v191, s87, v236
	v_pk_add_f32 v[44:45], v[44:45], v[190:191]
	v_lshlrev_b32_e32 v192, 16, v237
	v_and_b32_e32 v193, s87, v237
	v_pk_add_f32 v[46:47], v[46:47], v[192:193]
	v_lshlrev_b32_e32 v190, 16, v238
	v_and_b32_e32 v191, s87, v238
	v_pk_add_f32 v[40:41], v[40:41], v[190:191]
	v_lshlrev_b32_e32 v192, 16, v239
	v_and_b32_e32 v193, s87, v239
	v_pk_add_f32 v[42:43], v[42:43], v[192:193]
	v_lshlrev_b32_e32 v190, 16, v168
	v_and_b32_e32 v191, s87, v168
	v_pk_add_f32 v[36:37], v[36:37], v[190:191]
	v_lshlrev_b32_e32 v192, 16, v169
	v_and_b32_e32 v193, s87, v169
	v_pk_add_f32 v[38:39], v[38:39], v[192:193]
	v_lshlrev_b32_e32 v190, 16, v170
	v_and_b32_e32 v191, s87, v170
	v_pk_add_f32 v[32:33], v[32:33], v[190:191]
	v_lshlrev_b32_e32 v192, 16, v171
	v_and_b32_e32 v193, s87, v171
	v_pk_add_f32 v[34:35], v[34:35], v[192:193]
	v_cvt_pk_bf16_f32 v236, v44, v45
	v_cvt_pk_bf16_f32 v237, v46, v47
	v_cvt_pk_bf16_f32 v238, v40, v41
	v_cvt_pk_bf16_f32 v239, v42, v43
	v_cvt_pk_bf16_f32 v168, v36, v37
	v_cvt_pk_bf16_f32 v169, v38, v39
	v_cvt_pk_bf16_f32 v170, v32, v33
	v_cvt_pk_bf16_f32 v171, v34, v35
	v_mul_f32_e32 v157, v40, v40
	v_mul_f32_e32 v188, v32, v32
	v_fmac_f32_e32 v157, v41, v41
	v_fmac_f32_e32 v188, v33, v33
	v_fmac_f32_e32 v157, v42, v42
	v_fmac_f32_e32 v188, v34, v34
	v_fmac_f32_e32 v157, v43, v43
	v_fmac_f32_e32 v188, v35, v35
	v_fmac_f32_e32 v157, v44, v44
	v_fmac_f32_e32 v188, v36, v36
	v_fmac_f32_e32 v157, v45, v45
	v_fmac_f32_e32 v188, v37, v37
	v_fmac_f32_e32 v157, v46, v46
	v_fmac_f32_e32 v188, v38, v38
	v_fmac_f32_e32 v157, v47, v47
	v_fmac_f32_e32 v188, v39, v39
	v_add_f32_e32 v157, v157, v188
	v_cndmask_b32_e64 v32, v236, v168, s[4:5]
	v_cndmask_b32_e64 v33, v237, v169, s[4:5]
	v_cndmask_b32_e64 v34, v238, v170, s[4:5]
	v_cndmask_b32_e64 v35, v239, v171, s[4:5]
	v_mov_b32_dpp v36, v32 row_ror:8 row_mask:0xf bank_mask:0xf
	v_mov_b32_dpp v37, v33 row_ror:8 row_mask:0xf bank_mask:0xf
	v_mov_b32_dpp v38, v34 row_ror:8 row_mask:0xf bank_mask:0xf
	v_mov_b32_dpp v39, v35 row_ror:8 row_mask:0xf bank_mask:0xf
	v_cndmask_b32_e64 v168, v168, v36, s[4:5]
	v_cndmask_b32_e64 v236, v36, v236, s[4:5]
	v_cndmask_b32_e64 v169, v169, v37, s[4:5]
	v_cndmask_b32_e64 v237, v37, v237, s[4:5]
	v_cndmask_b32_e64 v170, v170, v38, s[4:5]
	v_cndmask_b32_e64 v238, v38, v238, s[4:5]
	v_cndmask_b32_e64 v171, v171, v39, s[4:5]
	v_cndmask_b32_e64 v239, v39, v239, s[4:5]
	global_store_dwordx4 v129, v[236:239], s[78:79]
	global_store_dwordx4 v131, v[168:171], s[78:79]
	s_add_u32 s78, s78, 0x8000
	s_addc_u32 s79, s79, 0
	s_waitcnt vmcnt(14)
	v_lshlrev_b32_e32 v190, 16, v172
	v_and_b32_e32 v191, s87, v172
	v_pk_add_f32 v[28:29], v[28:29], v[190:191]
	v_lshlrev_b32_e32 v192, 16, v173
	v_and_b32_e32 v193, s87, v173
	v_pk_add_f32 v[30:31], v[30:31], v[192:193]
	v_lshlrev_b32_e32 v190, 16, v174
	v_and_b32_e32 v191, s87, v174
	v_pk_add_f32 v[24:25], v[24:25], v[190:191]
	v_lshlrev_b32_e32 v192, 16, v175
	v_and_b32_e32 v193, s87, v175
	v_pk_add_f32 v[26:27], v[26:27], v[192:193]
	v_lshlrev_b32_e32 v190, 16, v176
	v_and_b32_e32 v191, s87, v176
	v_pk_add_f32 v[20:21], v[20:21], v[190:191]
	v_lshlrev_b32_e32 v192, 16, v177
	v_and_b32_e32 v193, s87, v177
	v_pk_add_f32 v[22:23], v[22:23], v[192:193]
	v_lshlrev_b32_e32 v190, 16, v178
	v_and_b32_e32 v191, s87, v178
	v_pk_add_f32 v[16:17], v[16:17], v[190:191]
	v_lshlrev_b32_e32 v192, 16, v179
	v_and_b32_e32 v193, s87, v179
	v_pk_add_f32 v[18:19], v[18:19], v[192:193]
	v_cvt_pk_bf16_f32 v172, v28, v29
	v_cvt_pk_bf16_f32 v173, v30, v31
	v_cvt_pk_bf16_f32 v174, v24, v25
	v_cvt_pk_bf16_f32 v175, v26, v27
	v_cvt_pk_bf16_f32 v176, v20, v21
	v_cvt_pk_bf16_f32 v177, v22, v23
	v_cvt_pk_bf16_f32 v178, v16, v17
	v_cvt_pk_bf16_f32 v179, v18, v19
	v_mul_f32_e32 v158, v24, v24
	v_mul_f32_e32 v188, v16, v16
	v_fmac_f32_e32 v158, v25, v25
	v_fmac_f32_e32 v188, v17, v17
	v_fmac_f32_e32 v158, v26, v26
	v_fmac_f32_e32 v188, v18, v18
	v_fmac_f32_e32 v158, v27, v27
	v_fmac_f32_e32 v188, v19, v19
	v_fmac_f32_e32 v158, v28, v28
	v_fmac_f32_e32 v188, v20, v20
	v_fmac_f32_e32 v158, v29, v29
	v_fmac_f32_e32 v188, v21, v21
	v_fmac_f32_e32 v158, v30, v30
	v_fmac_f32_e32 v188, v22, v22
	v_fmac_f32_e32 v158, v31, v31
	v_fmac_f32_e32 v188, v23, v23
	v_add_f32_e32 v158, v158, v188
	v_cndmask_b32_e64 v16, v172, v176, s[4:5]
	v_cndmask_b32_e64 v17, v173, v177, s[4:5]
	v_cndmask_b32_e64 v18, v174, v178, s[4:5]
	v_cndmask_b32_e64 v19, v175, v179, s[4:5]
	v_mov_b32_dpp v20, v16 row_ror:8 row_mask:0xf bank_mask:0xf
	v_mov_b32_dpp v21, v17 row_ror:8 row_mask:0xf bank_mask:0xf
	v_mov_b32_dpp v22, v18 row_ror:8 row_mask:0xf bank_mask:0xf
	v_mov_b32_dpp v23, v19 row_ror:8 row_mask:0xf bank_mask:0xf
	v_cndmask_b32_e64 v176, v176, v20, s[4:5]
	v_cndmask_b32_e64 v172, v20, v172, s[4:5]
	v_cndmask_b32_e64 v177, v177, v21, s[4:5]
	v_cndmask_b32_e64 v173, v21, v173, s[4:5]
	v_cndmask_b32_e64 v178, v178, v22, s[4:5]
	v_cndmask_b32_e64 v174, v22, v174, s[4:5]
	v_cndmask_b32_e64 v179, v179, v23, s[4:5]
	v_cndmask_b32_e64 v175, v23, v175, s[4:5]
	global_store_dwordx4 v129, v[172:175], s[78:79]
	global_store_dwordx4 v131, v[176:179], s[78:79]
	s_add_u32 s78, s78, 0x8000
	s_addc_u32 s79, s79, 0
	s_waitcnt vmcnt(14)
	v_lshlrev_b32_e32 v190, 16, v180
	v_and_b32_e32 v191, s87, v180
	v_pk_add_f32 v[12:13], v[12:13], v[190:191]
	v_lshlrev_b32_e32 v192, 16, v181
	v_and_b32_e32 v193, s87, v181
	v_pk_add_f32 v[14:15], v[14:15], v[192:193]
	v_lshlrev_b32_e32 v190, 16, v182
	v_and_b32_e32 v191, s87, v182
	v_pk_add_f32 v[8:9], v[8:9], v[190:191]
	v_lshlrev_b32_e32 v192, 16, v183
	v_and_b32_e32 v193, s87, v183
	v_pk_add_f32 v[10:11], v[10:11], v[192:193]
	v_lshlrev_b32_e32 v190, 16, v184
	v_and_b32_e32 v191, s87, v184
	v_pk_add_f32 v[4:5], v[4:5], v[190:191]
	v_lshlrev_b32_e32 v192, 16, v185
	v_and_b32_e32 v193, s87, v185
	v_pk_add_f32 v[6:7], v[6:7], v[192:193]
	v_lshlrev_b32_e32 v190, 16, v186
	v_and_b32_e32 v191, s87, v186
	v_pk_add_f32 v[0:1], v[0:1], v[190:191]
	v_lshlrev_b32_e32 v192, 16, v187
	v_and_b32_e32 v193, s87, v187
	v_pk_add_f32 v[2:3], v[2:3], v[192:193]
	v_cvt_pk_bf16_f32 v180, v12, v13
	v_cvt_pk_bf16_f32 v181, v14, v15
	v_cvt_pk_bf16_f32 v182, v8, v9
	v_cvt_pk_bf16_f32 v183, v10, v11
	v_cvt_pk_bf16_f32 v184, v4, v5
	v_cvt_pk_bf16_f32 v185, v6, v7
	v_cvt_pk_bf16_f32 v186, v0, v1
	v_cvt_pk_bf16_f32 v187, v2, v3
	v_mul_f32_e32 v159, v8, v8
	v_mul_f32_e32 v188, v0, v0
	v_fmac_f32_e32 v159, v9, v9
	v_fmac_f32_e32 v188, v1, v1
	v_fmac_f32_e32 v159, v10, v10
	v_fmac_f32_e32 v188, v2, v2
	v_fmac_f32_e32 v159, v11, v11
	v_fmac_f32_e32 v188, v3, v3
	v_fmac_f32_e32 v159, v12, v12
	v_fmac_f32_e32 v188, v4, v4
	v_fmac_f32_e32 v159, v13, v13
	v_fmac_f32_e32 v188, v5, v5
	v_fmac_f32_e32 v159, v14, v14
	v_fmac_f32_e32 v188, v6, v6
	v_fmac_f32_e32 v159, v15, v15
	v_fmac_f32_e32 v188, v7, v7
	v_add_f32_e32 v159, v159, v188
	v_cndmask_b32_e64 v0, v180, v184, s[4:5]
	v_cndmask_b32_e64 v1, v181, v185, s[4:5]
	v_cndmask_b32_e64 v2, v182, v186, s[4:5]
	v_cndmask_b32_e64 v3, v183, v187, s[4:5]
	v_mov_b32_dpp v4, v0 row_ror:8 row_mask:0xf bank_mask:0xf
	v_mov_b32_dpp v5, v1 row_ror:8 row_mask:0xf bank_mask:0xf
	v_mov_b32_dpp v6, v2 row_ror:8 row_mask:0xf bank_mask:0xf
	v_mov_b32_dpp v7, v3 row_ror:8 row_mask:0xf bank_mask:0xf
	v_cndmask_b32_e64 v184, v184, v4, s[4:5]
	v_cndmask_b32_e64 v180, v4, v180, s[4:5]
	v_cndmask_b32_e64 v185, v185, v5, s[4:5]
	v_cndmask_b32_e64 v181, v5, v181, s[4:5]
	v_cndmask_b32_e64 v186, v186, v6, s[4:5]
	v_cndmask_b32_e64 v182, v6, v182, s[4:5]
	v_cndmask_b32_e64 v187, v187, v7, s[4:5]
	v_cndmask_b32_e64 v183, v7, v183, s[4:5]
	global_store_dwordx4 v129, v[180:183], s[78:79]
	global_store_dwordx4 v131, v[184:187], s[78:79]
	ds_bpermute_b32 v112, v134, v152
	ds_bpermute_b32 v113, v134, v153
	ds_bpermute_b32 v114, v134, v154
	ds_bpermute_b32 v115, v134, v155
	ds_bpermute_b32 v116, v134, v156
	ds_bpermute_b32 v117, v134, v157
	ds_bpermute_b32 v118, v134, v158
	ds_bpermute_b32 v119, v134, v159
	s_waitcnt lgkmcnt(0)
	v_add_f32_e32 v152, v152, v112
	v_add_f32_e32 v153, v153, v113
	v_add_f32_e32 v154, v154, v114
	v_add_f32_e32 v155, v155, v115
	v_add_f32_e32 v156, v156, v116
	v_add_f32_e32 v157, v157, v117
	v_add_f32_e32 v158, v158, v118
	v_add_f32_e32 v159, v159, v119
	ds_bpermute_b32 v112, v135, v152
	ds_bpermute_b32 v113, v135, v153
	ds_bpermute_b32 v114, v135, v154
	ds_bpermute_b32 v115, v135, v155
	ds_bpermute_b32 v116, v135, v156
	ds_bpermute_b32 v117, v135, v157
	ds_bpermute_b32 v118, v135, v158
	ds_bpermute_b32 v119, v135, v159
	s_waitcnt lgkmcnt(0)
	v_add_f32_e32 v152, v152, v112
	v_add_f32_e32 v153, v153, v113
	v_add_f32_e32 v154, v154, v114
	v_add_f32_e32 v155, v155, v115
	v_add_f32_e32 v156, v156, v116
	v_add_f32_e32 v157, v157, v117
	v_add_f32_e32 v158, v158, v118
	v_add_f32_e32 v159, v159, v119
	s_and_saveexec_b64 s[48:49], s[2:3]
	global_store_dword v130, v152, s[0:1]
	global_store_dword v130, v153, s[0:1] offset:1024
	global_store_dword v130, v154, s[0:1] offset:2048
	global_store_dword v130, v155, s[0:1] offset:3072
	global_store_dword v130, v156, s[80:81]
	global_store_dword v130, v157, s[80:81] offset:1024
	global_store_dword v130, v158, s[80:81] offset:2048
	global_store_dword v130, v159, s[80:81] offset:3072
	s_or_b64 exec, exec, s[48:49]
	s_branch .Lf9_next
